# write-through variant: in-proj act-epilogue stores use sc1 instead of nt (to shrink the release fence at the grid barrier)
# baseline (speedup 1.0000x reference)
; #define GAS __attribute__((address_space(1)))
; __device__ __forceinline__ float fsigmoid(float x) { return frcp(1.0f + fexp2(-x * LOG2E)); }
; #define EPI_FOR_ROWS for (int ai = 0; ai < 2; ++ai) _Pragma("unroll") for (int m = 0; m < 4; ++m)
; __device__ __forceinline__ v4u pack8(const f32x4 a, const f32x4 b) { v4u w; w.x = cvt_pk_bf16(a[0], a[1]); w.y = cvt_pk_bf16(a[2], a[3]); w.z = cvt_pk_bf16(b[0], b[1]); w.w = cvt_pk_bf16(b[2], b[3]); return w; }
; #define NT_ST(p, v) __builtin_nontemporal_store((v), (p))
;     __device__ __forceinline__ void operator()(Acc& acc, const Unit& u, int wr, int wc, int fr, int fq, LAS unsigned char* lds) const {
;     ...
;         size_t off; int act;
;         switch (grp) {
;             case 0: off = WS_UA; act = 0; break;   case 1: off = WS_SGA; act = 1; break;  case 5: off = WS_SGB; act = 1; break;
;             case 7: off = WS_QC; act = 1; break;   case 8: off = WS_IC; act = 0; break;   case 9: off = WS_SGC; act = 1; break;
;             default: off = WS_GATE + (size_t)(grp - 10) * RB16; act = 2; break;
;         }
;         GAS bf16* dst = (GAS bf16*)(ws + off);
; #pragma unroll
;         EPI_FOR_ROWS { const int row = row0 + ai * 128 + m * 16;
; #pragma unroll
;             for (int bj = 0; bj < 2; ++bj) { f32x4 a = acc[ai][bj][m][0], b = acc[ai][bj][m][1];
;                 if (act) {
; #pragma unroll
;                     for (int j = 0; j < 4; ++j) { const float sa = fsigmoid(a[j]), sb = fsigmoid(b[j]);
;                         a[j] = act == 1 ? a[j] * sa : fmaxf(sa, 1e-30f); b[j] = act == 1 ? b[j] * sb : fmaxf(sb, 1e-30f); } }
;                 NT_ST((GAS v4u*)(dst + (size_t)row * 1024 + cg0 + bj * 128), pack8(a, b)); } }
.LBB0_236:
	v_readlane_b32 s34, v240, 13
	v_readlane_b32 s35, v240, 12
	v_ashrrev_i32_e32 v153, 31, v152
	v_ashrrev_i32_e32 v155, 31, v154
	s_add_u32 s34, s34, s52
	s_addc_u32 s35, s35, s53
	v_lshlrev_b64 v[158:159], 11, v[154:155]
	v_lshl_add_u64 v[156:157], v[152:153], 1, s[34:35]
	s_mov_b32 s24, 0xbfb8aa3b
	s_mov_b32 s25, 0xda24260
	v_lshl_add_u64 v[158:159], v[156:157], 0, v[158:159]
	s_and_b64 vcc, exec, s[64:65]
	s_cbranch_vccnz .Lep_none
	s_and_b64 vcc, exec, s[62:63]
	s_cbranch_vccnz .Lep_silu
	v_pk_mul_f32 v[128:129], v[124:125], s[24:25] op_sel_hi:[1,0]
	v_pk_mul_f32 v[130:131], v[126:127], s[24:25] op_sel_hi:[1,0]
	v_pk_mul_f32 v[132:133], v[120:121], s[24:25] op_sel_hi:[1,0]
	v_pk_mul_f32 v[134:135], v[122:123], s[24:25] op_sel_hi:[1,0]
	v_pk_mul_f32 v[160:161], v[116:117], s[24:25] op_sel_hi:[1,0]
	v_pk_mul_f32 v[162:163], v[118:119], s[24:25] op_sel_hi:[1,0]
	v_pk_mul_f32 v[164:165], v[112:113], s[24:25] op_sel_hi:[1,0]
	v_pk_mul_f32 v[166:167], v[114:115], s[24:25] op_sel_hi:[1,0]
	v_exp_f32_e32 v128, v128
	v_exp_f32_e32 v129, v129
	v_exp_f32_e32 v130, v130
	v_exp_f32_e32 v131, v131
	v_exp_f32_e32 v132, v132
	v_exp_f32_e32 v133, v133
	v_exp_f32_e32 v134, v134
	v_exp_f32_e32 v135, v135
	v_exp_f32_e32 v160, v160
	v_exp_f32_e32 v161, v161
	v_exp_f32_e32 v162, v162
	v_exp_f32_e32 v163, v163
	v_exp_f32_e32 v164, v164
	v_exp_f32_e32 v165, v165
	v_exp_f32_e32 v166, v166
	v_exp_f32_e32 v167, v167
	v_pk_add_f32 v[128:129], v[128:129], 1.0 op_sel_hi:[1,0]
	v_pk_add_f32 v[130:131], v[130:131], 1.0 op_sel_hi:[1,0]
	v_pk_add_f32 v[132:133], v[132:133], 1.0 op_sel_hi:[1,0]
	v_pk_add_f32 v[134:135], v[134:135], 1.0 op_sel_hi:[1,0]
	v_pk_add_f32 v[160:161], v[160:161], 1.0 op_sel_hi:[1,0]
	v_pk_add_f32 v[162:163], v[162:163], 1.0 op_sel_hi:[1,0]
	v_pk_add_f32 v[164:165], v[164:165], 1.0 op_sel_hi:[1,0]
	v_pk_add_f32 v[166:167], v[166:167], 1.0 op_sel_hi:[1,0]
	v_rcp_f32_e32 v128, v128
	v_rcp_f32_e32 v129, v129
	v_rcp_f32_e32 v130, v130
	v_rcp_f32_e32 v131, v131
	v_rcp_f32_e32 v132, v132
	v_rcp_f32_e32 v133, v133
	v_rcp_f32_e32 v134, v134
	v_rcp_f32_e32 v135, v135
	v_rcp_f32_e32 v160, v160
	v_rcp_f32_e32 v161, v161
	v_rcp_f32_e32 v162, v162
	v_rcp_f32_e32 v163, v163
	v_rcp_f32_e32 v164, v164
	v_rcp_f32_e32 v165, v165
	v_rcp_f32_e32 v166, v166
	v_rcp_f32_e32 v167, v167
	v_max_f32_e32 v128, s25, v128
	v_max_f32_e32 v129, s25, v129
	v_max_f32_e32 v130, s25, v130
	v_max_f32_e32 v131, s25, v131
	v_max_f32_e32 v132, s25, v132
	v_max_f32_e32 v133, s25, v133
	v_max_f32_e32 v134, s25, v134
	v_max_f32_e32 v135, s25, v135
	v_max_f32_e32 v160, s25, v160
	v_max_f32_e32 v161, s25, v161
	v_max_f32_e32 v162, s25, v162
	v_max_f32_e32 v163, s25, v163
	v_max_f32_e32 v164, s25, v164
	v_max_f32_e32 v165, s25, v165
	v_max_f32_e32 v166, s25, v166
	v_max_f32_e32 v167, s25, v167
	v_cvt_pk_bf16_f32 v128, v128, v129
	v_cvt_pk_bf16_f32 v129, v130, v131
	v_cvt_pk_bf16_f32 v130, v132, v133
	v_cvt_pk_bf16_f32 v131, v134, v135
	v_cvt_pk_bf16_f32 v160, v160, v161
	global_store_dwordx4 v[158:159], v[128:131], off sc1
	v_cvt_pk_bf16_f32 v161, v162, v163
	v_cvt_pk_bf16_f32 v162, v164, v165
	v_cvt_pk_bf16_f32 v163, v166, v167
	s_nop 0
	global_store_dwordx4 v[158:159], v[160:163], off offset:256 sc1
	s_mov_b64 s[34:35], 0x8000
	v_pk_mul_f32 v[128:129], v[108:109], s[24:25] op_sel_hi:[1,0]
	v_pk_mul_f32 v[130:131], v[110:111], s[24:25] op_sel_hi:[1,0]
	v_pk_mul_f32 v[132:133], v[104:105], s[24:25] op_sel_hi:[1,0]
	v_pk_mul_f32 v[134:135], v[106:107], s[24:25] op_sel_hi:[1,0]
	v_pk_mul_f32 v[160:161], v[100:101], s[24:25] op_sel_hi:[1,0]
	v_pk_mul_f32 v[162:163], v[102:103], s[24:25] op_sel_hi:[1,0]
	v_pk_mul_f32 v[164:165], v[96:97], s[24:25] op_sel_hi:[1,0]
	v_pk_mul_f32 v[166:167], v[98:99], s[24:25] op_sel_hi:[1,0]
	v_exp_f32_e32 v128, v128
	v_exp_f32_e32 v129, v129
	v_exp_f32_e32 v130, v130
	v_exp_f32_e32 v131, v131
	v_exp_f32_e32 v132, v132
	v_exp_f32_e32 v133, v133
	v_exp_f32_e32 v134, v134
	v_exp_f32_e32 v135, v135
	v_exp_f32_e32 v160, v160
	v_exp_f32_e32 v161, v161
	v_exp_f32_e32 v162, v162
	v_exp_f32_e32 v163, v163
	v_exp_f32_e32 v164, v164
	v_exp_f32_e32 v165, v165
	v_exp_f32_e32 v166, v166
	v_exp_f32_e32 v167, v167
	v_lshl_add_u64 v[168:169], v[158:159], 0, s[34:35]
	v_pk_add_f32 v[128:129], v[128:129], 1.0 op_sel_hi:[1,0]
	v_pk_add_f32 v[130:131], v[130:131], 1.0 op_sel_hi:[1,0]
	v_pk_add_f32 v[132:133], v[132:133], 1.0 op_sel_hi:[1,0]
	v_pk_add_f32 v[134:135], v[134:135], 1.0 op_sel_hi:[1,0]
	v_pk_add_f32 v[160:161], v[160:161], 1.0 op_sel_hi:[1,0]
	v_pk_add_f32 v[162:163], v[162:163], 1.0 op_sel_hi:[1,0]
	v_pk_add_f32 v[164:165], v[164:165], 1.0 op_sel_hi:[1,0]
	v_pk_add_f32 v[166:167], v[166:167], 1.0 op_sel_hi:[1,0]
	v_rcp_f32_e32 v128, v128
	v_rcp_f32_e32 v129, v129
	v_rcp_f32_e32 v130, v130
	v_rcp_f32_e32 v131, v131
	v_rcp_f32_e32 v132, v132
	v_rcp_f32_e32 v133, v133
	v_rcp_f32_e32 v134, v134
	v_rcp_f32_e32 v135, v135
	v_rcp_f32_e32 v160, v160
	v_rcp_f32_e32 v161, v161
	v_rcp_f32_e32 v162, v162
	v_rcp_f32_e32 v163, v163
	v_rcp_f32_e32 v164, v164
	v_rcp_f32_e32 v165, v165
	v_rcp_f32_e32 v166, v166
	v_rcp_f32_e32 v167, v167
	v_max_f32_e32 v128, s25, v128
	v_max_f32_e32 v129, s25, v129
	v_max_f32_e32 v130, s25, v130
	v_max_f32_e32 v131, s25, v131
	v_max_f32_e32 v132, s25, v132
	v_max_f32_e32 v133, s25, v133
	v_max_f32_e32 v134, s25, v134
	v_max_f32_e32 v135, s25, v135
	v_max_f32_e32 v160, s25, v160
	v_max_f32_e32 v161, s25, v161
	v_max_f32_e32 v162, s25, v162
	v_max_f32_e32 v163, s25, v163
	v_max_f32_e32 v164, s25, v164
	v_max_f32_e32 v165, s25, v165
	v_max_f32_e32 v166, s25, v166
	v_max_f32_e32 v167, s25, v167
	v_cvt_pk_bf16_f32 v128, v128, v129
; #define GAS __attribute__((address_space(1)))
; __device__ __forceinline__ float fsigmoid(float x) { return frcp(1.0f + fexp2(-x * LOG2E)); }
; __device__ __forceinline__ v4u pack8(const f32x4 a, const f32x4 b) { v4u w; w.x = cvt_pk_bf16(a[0], a[1]); w.y = cvt_pk_bf16(a[2], a[3]); w.z = cvt_pk_bf16(b[0], b[1]); w.w = cvt_pk_bf16(b[2], b[3]); return w; }
; #define NT_ST(p, v) __builtin_nontemporal_store((v), (p))
;     __device__ __forceinline__ void operator()(Acc& acc, const Unit& u, int wr, int wc, int fr, int fq, LAS unsigned char* lds) const {
;     ...
;                     for (int j = 0; j < 4; ++j) { const float sa = fsigmoid(a[j]), sb = fsigmoid(b[j]);
;                         a[j] = act == 1 ? a[j] * sa : fmaxf(sa, 1e-30f); b[j] = act == 1 ? b[j] * sb : fmaxf(sb, 1e-30f); } }
;                 NT_ST((GAS v4u*)(dst + (size_t)row * 1024 + cg0 + bj * 128), pack8(a, b)); } }
	v_cvt_pk_bf16_f32 v129, v130, v131
	v_cvt_pk_bf16_f32 v130, v132, v133
	v_cvt_pk_bf16_f32 v131, v134, v135
	v_cvt_pk_bf16_f32 v160, v160, v161
	global_store_dwordx4 v[168:169], v[128:131], off sc1
	v_cvt_pk_bf16_f32 v161, v162, v163
	v_cvt_pk_bf16_f32 v162, v164, v165
	v_cvt_pk_bf16_f32 v163, v166, v167
	s_nop 0
	global_store_dwordx4 v[168:169], v[160:163], off offset:256 sc1
	s_mov_b64 s[34:35], 0x10000
	v_pk_mul_f32 v[128:129], v[92:93], s[24:25] op_sel_hi:[1,0]
	v_pk_mul_f32 v[130:131], v[94:95], s[24:25] op_sel_hi:[1,0]
	v_pk_mul_f32 v[132:133], v[88:89], s[24:25] op_sel_hi:[1,0]
	v_pk_mul_f32 v[134:135], v[90:91], s[24:25] op_sel_hi:[1,0]
	v_pk_mul_f32 v[160:161], v[84:85], s[24:25] op_sel_hi:[1,0]
	v_pk_mul_f32 v[162:163], v[86:87], s[24:25] op_sel_hi:[1,0]
	v_pk_mul_f32 v[164:165], v[80:81], s[24:25] op_sel_hi:[1,0]
	v_pk_mul_f32 v[166:167], v[82:83], s[24:25] op_sel_hi:[1,0]
	v_exp_f32_e32 v128, v128
	v_exp_f32_e32 v129, v129
	v_exp_f32_e32 v130, v130
	v_exp_f32_e32 v131, v131
	v_exp_f32_e32 v132, v132
	v_exp_f32_e32 v133, v133
	v_exp_f32_e32 v134, v134
	v_exp_f32_e32 v135, v135
	v_exp_f32_e32 v160, v160
	v_exp_f32_e32 v161, v161
	v_exp_f32_e32 v162, v162
	v_exp_f32_e32 v163, v163
	v_exp_f32_e32 v164, v164
	v_exp_f32_e32 v165, v165
	v_exp_f32_e32 v166, v166
	v_exp_f32_e32 v167, v167
	v_lshl_add_u64 v[170:171], v[158:159], 0, s[34:35]
	v_pk_add_f32 v[128:129], v[128:129], 1.0 op_sel_hi:[1,0]
	v_pk_add_f32 v[130:131], v[130:131], 1.0 op_sel_hi:[1,0]
	v_pk_add_f32 v[132:133], v[132:133], 1.0 op_sel_hi:[1,0]
	v_pk_add_f32 v[134:135], v[134:135], 1.0 op_sel_hi:[1,0]
	v_pk_add_f32 v[160:161], v[160:161], 1.0 op_sel_hi:[1,0]
	v_pk_add_f32 v[162:163], v[162:163], 1.0 op_sel_hi:[1,0]
	v_pk_add_f32 v[164:165], v[164:165], 1.0 op_sel_hi:[1,0]
	v_pk_add_f32 v[166:167], v[166:167], 1.0 op_sel_hi:[1,0]
	v_rcp_f32_e32 v128, v128
	v_rcp_f32_e32 v129, v129
	v_rcp_f32_e32 v130, v130
	v_rcp_f32_e32 v131, v131
	v_rcp_f32_e32 v132, v132
	v_rcp_f32_e32 v133, v133
	v_rcp_f32_e32 v134, v134
	v_rcp_f32_e32 v135, v135
	v_rcp_f32_e32 v160, v160
	v_rcp_f32_e32 v161, v161
	v_rcp_f32_e32 v162, v162
	v_rcp_f32_e32 v163, v163
	v_rcp_f32_e32 v164, v164
	v_rcp_f32_e32 v165, v165
	v_rcp_f32_e32 v166, v166
	v_rcp_f32_e32 v167, v167
	v_max_f32_e32 v128, s25, v128
	v_max_f32_e32 v129, s25, v129
	v_max_f32_e32 v130, s25, v130
	v_max_f32_e32 v131, s25, v131
	v_max_f32_e32 v132, s25, v132
	v_max_f32_e32 v133, s25, v133
	v_max_f32_e32 v134, s25, v134
	v_max_f32_e32 v135, s25, v135
	v_max_f32_e32 v160, s25, v160
	v_max_f32_e32 v161, s25, v161
	v_max_f32_e32 v162, s25, v162
	v_max_f32_e32 v163, s25, v163
	v_max_f32_e32 v164, s25, v164
	v_max_f32_e32 v165, s25, v165
	v_max_f32_e32 v166, s25, v166
	v_max_f32_e32 v167, s25, v167
	v_cvt_pk_bf16_f32 v128, v128, v129
	v_cvt_pk_bf16_f32 v129, v130, v131
	v_cvt_pk_bf16_f32 v130, v132, v133
	v_cvt_pk_bf16_f32 v131, v134, v135
	v_cvt_pk_bf16_f32 v160, v160, v161
	global_store_dwordx4 v[170:171], v[128:131], off sc1
	v_cvt_pk_bf16_f32 v161, v162, v163
	v_cvt_pk_bf16_f32 v162, v164, v165
	v_cvt_pk_bf16_f32 v163, v166, v167
	s_nop 0
	global_store_dwordx4 v[170:171], v[160:163], off offset:256 sc1
	s_mov_b64 s[34:35], 0x18000
	v_pk_mul_f32 v[128:129], v[76:77], s[24:25] op_sel_hi:[1,0]
	v_pk_mul_f32 v[130:131], v[78:79], s[24:25] op_sel_hi:[1,0]
	v_pk_mul_f32 v[132:133], v[72:73], s[24:25] op_sel_hi:[1,0]
	v_pk_mul_f32 v[134:135], v[74:75], s[24:25] op_sel_hi:[1,0]
	v_pk_mul_f32 v[160:161], v[68:69], s[24:25] op_sel_hi:[1,0]
	v_pk_mul_f32 v[162:163], v[70:71], s[24:25] op_sel_hi:[1,0]
	v_pk_mul_f32 v[164:165], v[64:65], s[24:25] op_sel_hi:[1,0]
	v_pk_mul_f32 v[166:167], v[66:67], s[24:25] op_sel_hi:[1,0]
	v_exp_f32_e32 v128, v128
	v_exp_f32_e32 v129, v129
	v_exp_f32_e32 v130, v130
	v_exp_f32_e32 v131, v131
	v_exp_f32_e32 v132, v132
	v_exp_f32_e32 v133, v133
	v_exp_f32_e32 v134, v134
	v_exp_f32_e32 v135, v135
	v_exp_f32_e32 v160, v160
	v_exp_f32_e32 v161, v161
	v_exp_f32_e32 v162, v162
	v_exp_f32_e32 v163, v163
	v_exp_f32_e32 v164, v164
	v_exp_f32_e32 v165, v165
	v_exp_f32_e32 v166, v166
	v_exp_f32_e32 v167, v167
	v_lshl_add_u64 v[168:169], v[158:159], 0, s[34:35]
	v_pk_add_f32 v[128:129], v[128:129], 1.0 op_sel_hi:[1,0]
	v_pk_add_f32 v[130:131], v[130:131], 1.0 op_sel_hi:[1,0]
	v_pk_add_f32 v[132:133], v[132:133], 1.0 op_sel_hi:[1,0]
	v_pk_add_f32 v[134:135], v[134:135], 1.0 op_sel_hi:[1,0]
	v_pk_add_f32 v[160:161], v[160:161], 1.0 op_sel_hi:[1,0]
	v_pk_add_f32 v[162:163], v[162:163], 1.0 op_sel_hi:[1,0]
	v_pk_add_f32 v[164:165], v[164:165], 1.0 op_sel_hi:[1,0]
	v_pk_add_f32 v[166:167], v[166:167], 1.0 op_sel_hi:[1,0]
	v_rcp_f32_e32 v128, v128
	v_rcp_f32_e32 v129, v129
	v_rcp_f32_e32 v130, v130
	v_rcp_f32_e32 v131, v131
	v_rcp_f32_e32 v132, v132
	v_rcp_f32_e32 v133, v133
	v_rcp_f32_e32 v134, v134
	v_rcp_f32_e32 v135, v135
	v_rcp_f32_e32 v160, v160
	v_rcp_f32_e32 v161, v161
	v_rcp_f32_e32 v162, v162
	v_rcp_f32_e32 v163, v163
	v_rcp_f32_e32 v164, v164
	v_rcp_f32_e32 v165, v165
	v_rcp_f32_e32 v166, v166
	v_rcp_f32_e32 v167, v167
	v_max_f32_e32 v128, s25, v128
	v_max_f32_e32 v129, s25, v129
	v_max_f32_e32 v130, s25, v130
	v_max_f32_e32 v131, s25, v131
	v_max_f32_e32 v132, s25, v132
	v_max_f32_e32 v133, s25, v133
	v_max_f32_e32 v134, s25, v134
	v_max_f32_e32 v135, s25, v135
	v_max_f32_e32 v160, s25, v160
	v_max_f32_e32 v161, s25, v161
	v_max_f32_e32 v162, s25, v162
	v_max_f32_e32 v163, s25, v163
	v_max_f32_e32 v164, s25, v164
	v_max_f32_e32 v165, s25, v165
	v_max_f32_e32 v166, s25, v166
	v_max_f32_e32 v167, s25, v167
	v_cvt_pk_bf16_f32 v128, v128, v129
	v_cvt_pk_bf16_f32 v129, v130, v131
	v_cvt_pk_bf16_f32 v130, v132, v133
; #define GAS __attribute__((address_space(1)))
; __device__ __forceinline__ float fsigmoid(float x) { return frcp(1.0f + fexp2(-x * LOG2E)); }
; __device__ __forceinline__ v4u pack8(const f32x4 a, const f32x4 b) { v4u w; w.x = cvt_pk_bf16(a[0], a[1]); w.y = cvt_pk_bf16(a[2], a[3]); w.z = cvt_pk_bf16(b[0], b[1]); w.w = cvt_pk_bf16(b[2], b[3]); return w; }
; #define NT_ST(p, v) __builtin_nontemporal_store((v), (p))
;     __device__ __forceinline__ void operator()(Acc& acc, const Unit& u, int wr, int wc, int fr, int fq, LAS unsigned char* lds) const {
;     ...
;                     for (int j = 0; j < 4; ++j) { const float sa = fsigmoid(a[j]), sb = fsigmoid(b[j]);
;                         a[j] = act == 1 ? a[j] * sa : fmaxf(sa, 1e-30f); b[j] = act == 1 ? b[j] * sb : fmaxf(sb, 1e-30f); } }
;                 NT_ST((GAS v4u*)(dst + (size_t)row * 1024 + cg0 + bj * 128), pack8(a, b)); } }
	v_cvt_pk_bf16_f32 v131, v134, v135
	v_cvt_pk_bf16_f32 v160, v160, v161
	global_store_dwordx4 v[168:169], v[128:131], off sc1
	v_cvt_pk_bf16_f32 v161, v162, v163
	v_cvt_pk_bf16_f32 v162, v164, v165
	v_cvt_pk_bf16_f32 v163, v166, v167
	s_nop 0
	global_store_dwordx4 v[168:169], v[160:163], off offset:256 sc1
	s_mov_b64 s[34:35], 0x40000
	v_pk_mul_f32 v[128:129], v[60:61], s[24:25] op_sel_hi:[1,0]
	v_pk_mul_f32 v[130:131], v[62:63], s[24:25] op_sel_hi:[1,0]
	v_pk_mul_f32 v[132:133], v[56:57], s[24:25] op_sel_hi:[1,0]
	v_pk_mul_f32 v[134:135], v[58:59], s[24:25] op_sel_hi:[1,0]
	v_pk_mul_f32 v[160:161], v[52:53], s[24:25] op_sel_hi:[1,0]
	v_pk_mul_f32 v[162:163], v[54:55], s[24:25] op_sel_hi:[1,0]
	v_pk_mul_f32 v[164:165], v[48:49], s[24:25] op_sel_hi:[1,0]
	v_pk_mul_f32 v[166:167], v[50:51], s[24:25] op_sel_hi:[1,0]
	v_exp_f32_e32 v128, v128
	v_exp_f32_e32 v129, v129
	v_exp_f32_e32 v130, v130
	v_exp_f32_e32 v131, v131
	v_exp_f32_e32 v132, v132
	v_exp_f32_e32 v133, v133
	v_exp_f32_e32 v134, v134
	v_exp_f32_e32 v135, v135
	v_exp_f32_e32 v160, v160
	v_exp_f32_e32 v161, v161
	v_exp_f32_e32 v162, v162
	v_exp_f32_e32 v163, v163
	v_exp_f32_e32 v164, v164
	v_exp_f32_e32 v165, v165
	v_exp_f32_e32 v166, v166
	v_exp_f32_e32 v167, v167
	v_lshl_add_u64 v[170:171], v[158:159], 0, s[34:35]
	v_pk_add_f32 v[128:129], v[128:129], 1.0 op_sel_hi:[1,0]
	v_pk_add_f32 v[130:131], v[130:131], 1.0 op_sel_hi:[1,0]
	v_pk_add_f32 v[132:133], v[132:133], 1.0 op_sel_hi:[1,0]
	v_pk_add_f32 v[134:135], v[134:135], 1.0 op_sel_hi:[1,0]
	v_pk_add_f32 v[160:161], v[160:161], 1.0 op_sel_hi:[1,0]
	v_pk_add_f32 v[162:163], v[162:163], 1.0 op_sel_hi:[1,0]
	v_pk_add_f32 v[164:165], v[164:165], 1.0 op_sel_hi:[1,0]
	v_pk_add_f32 v[166:167], v[166:167], 1.0 op_sel_hi:[1,0]
	v_rcp_f32_e32 v128, v128
	v_rcp_f32_e32 v129, v129
	v_rcp_f32_e32 v130, v130
	v_rcp_f32_e32 v131, v131
	v_rcp_f32_e32 v132, v132
	v_rcp_f32_e32 v133, v133
	v_rcp_f32_e32 v134, v134
	v_rcp_f32_e32 v135, v135
	v_rcp_f32_e32 v160, v160
	v_rcp_f32_e32 v161, v161
	v_rcp_f32_e32 v162, v162
	v_rcp_f32_e32 v163, v163
	v_rcp_f32_e32 v164, v164
	v_rcp_f32_e32 v165, v165
	v_rcp_f32_e32 v166, v166
	v_rcp_f32_e32 v167, v167
	v_max_f32_e32 v128, s25, v128
	v_max_f32_e32 v129, s25, v129
	v_max_f32_e32 v130, s25, v130
	v_max_f32_e32 v131, s25, v131
	v_max_f32_e32 v132, s25, v132
	v_max_f32_e32 v133, s25, v133
	v_max_f32_e32 v134, s25, v134
	v_max_f32_e32 v135, s25, v135
	v_max_f32_e32 v160, s25, v160
	v_max_f32_e32 v161, s25, v161
	v_max_f32_e32 v162, s25, v162
	v_max_f32_e32 v163, s25, v163
	v_max_f32_e32 v164, s25, v164
	v_max_f32_e32 v165, s25, v165
	v_max_f32_e32 v166, s25, v166
	v_max_f32_e32 v167, s25, v167
	v_cvt_pk_bf16_f32 v128, v128, v129
	v_cvt_pk_bf16_f32 v129, v130, v131
	v_cvt_pk_bf16_f32 v130, v132, v133
	v_cvt_pk_bf16_f32 v131, v134, v135
	v_cvt_pk_bf16_f32 v160, v160, v161
	global_store_dwordx4 v[170:171], v[128:131], off sc1
	v_cvt_pk_bf16_f32 v161, v162, v163
	v_cvt_pk_bf16_f32 v162, v164, v165
	v_cvt_pk_bf16_f32 v163, v166, v167
	s_nop 0
	global_store_dwordx4 v[170:171], v[160:163], off offset:256 sc1
	s_mov_b64 s[34:35], 0x48000
	v_pk_mul_f32 v[128:129], v[44:45], s[24:25] op_sel_hi:[1,0]
	v_pk_mul_f32 v[130:131], v[46:47], s[24:25] op_sel_hi:[1,0]
	v_pk_mul_f32 v[132:133], v[40:41], s[24:25] op_sel_hi:[1,0]
	v_pk_mul_f32 v[134:135], v[42:43], s[24:25] op_sel_hi:[1,0]
	v_pk_mul_f32 v[160:161], v[36:37], s[24:25] op_sel_hi:[1,0]
	v_pk_mul_f32 v[162:163], v[38:39], s[24:25] op_sel_hi:[1,0]
	v_pk_mul_f32 v[164:165], v[32:33], s[24:25] op_sel_hi:[1,0]
	v_pk_mul_f32 v[166:167], v[34:35], s[24:25] op_sel_hi:[1,0]
	v_exp_f32_e32 v128, v128
	v_exp_f32_e32 v129, v129
	v_exp_f32_e32 v130, v130
	v_exp_f32_e32 v131, v131
	v_exp_f32_e32 v132, v132
	v_exp_f32_e32 v133, v133
	v_exp_f32_e32 v134, v134
	v_exp_f32_e32 v135, v135
	v_exp_f32_e32 v160, v160
	v_exp_f32_e32 v161, v161
	v_exp_f32_e32 v162, v162
	v_exp_f32_e32 v163, v163
	v_exp_f32_e32 v164, v164
	v_exp_f32_e32 v165, v165
	v_exp_f32_e32 v166, v166
	v_exp_f32_e32 v167, v167
	v_lshl_add_u64 v[168:169], v[158:159], 0, s[34:35]
	v_pk_add_f32 v[128:129], v[128:129], 1.0 op_sel_hi:[1,0]
	v_pk_add_f32 v[130:131], v[130:131], 1.0 op_sel_hi:[1,0]
	v_pk_add_f32 v[132:133], v[132:133], 1.0 op_sel_hi:[1,0]
	v_pk_add_f32 v[134:135], v[134:135], 1.0 op_sel_hi:[1,0]
	v_pk_add_f32 v[160:161], v[160:161], 1.0 op_sel_hi:[1,0]
	v_pk_add_f32 v[162:163], v[162:163], 1.0 op_sel_hi:[1,0]
	v_pk_add_f32 v[164:165], v[164:165], 1.0 op_sel_hi:[1,0]
	v_pk_add_f32 v[166:167], v[166:167], 1.0 op_sel_hi:[1,0]
	v_rcp_f32_e32 v128, v128
	v_rcp_f32_e32 v129, v129
	v_rcp_f32_e32 v130, v130
	v_rcp_f32_e32 v131, v131
	v_rcp_f32_e32 v132, v132
	v_rcp_f32_e32 v133, v133
	v_rcp_f32_e32 v134, v134
	v_rcp_f32_e32 v135, v135
	v_rcp_f32_e32 v160, v160
	v_rcp_f32_e32 v161, v161
	v_rcp_f32_e32 v162, v162
	v_rcp_f32_e32 v163, v163
	v_rcp_f32_e32 v164, v164
	v_rcp_f32_e32 v165, v165
	v_rcp_f32_e32 v166, v166
	v_rcp_f32_e32 v167, v167
	v_max_f32_e32 v128, s25, v128
	v_max_f32_e32 v129, s25, v129
	v_max_f32_e32 v130, s25, v130
	v_max_f32_e32 v131, s25, v131
	v_max_f32_e32 v132, s25, v132
	v_max_f32_e32 v133, s25, v133
	v_max_f32_e32 v134, s25, v134
	v_max_f32_e32 v135, s25, v135
	v_max_f32_e32 v160, s25, v160
	v_max_f32_e32 v161, s25, v161
	v_max_f32_e32 v162, s25, v162
	v_max_f32_e32 v163, s25, v163
	v_max_f32_e32 v164, s25, v164
	v_max_f32_e32 v165, s25, v165
	v_max_f32_e32 v166, s25, v166
	v_max_f32_e32 v167, s25, v167
	v_cvt_pk_bf16_f32 v128, v128, v129
	v_cvt_pk_bf16_f32 v129, v130, v131
	v_cvt_pk_bf16_f32 v130, v132, v133
	v_cvt_pk_bf16_f32 v131, v134, v135
	v_cvt_pk_bf16_f32 v160, v160, v161
; #define GAS __attribute__((address_space(1)))
; __device__ __forceinline__ float fsigmoid(float x) { return frcp(1.0f + fexp2(-x * LOG2E)); }
; __device__ __forceinline__ v4u pack8(const f32x4 a, const f32x4 b) { v4u w; w.x = cvt_pk_bf16(a[0], a[1]); w.y = cvt_pk_bf16(a[2], a[3]); w.z = cvt_pk_bf16(b[0], b[1]); w.w = cvt_pk_bf16(b[2], b[3]); return w; }
; #define NT_ST(p, v) __builtin_nontemporal_store((v), (p))
;     __device__ __forceinline__ void operator()(Acc& acc, const Unit& u, int wr, int wc, int fr, int fq, LAS unsigned char* lds) const {
;     ...
;                     for (int j = 0; j < 4; ++j) { const float sa = fsigmoid(a[j]), sb = fsigmoid(b[j]);
;                         a[j] = act == 1 ? a[j] * sa : fmaxf(sa, 1e-30f); b[j] = act == 1 ? b[j] * sb : fmaxf(sb, 1e-30f); } }
;                 NT_ST((GAS v4u*)(dst + (size_t)row * 1024 + cg0 + bj * 128), pack8(a, b)); } }
	global_store_dwordx4 v[168:169], v[128:131], off sc1
	v_cvt_pk_bf16_f32 v161, v162, v163
	v_cvt_pk_bf16_f32 v162, v164, v165
	v_cvt_pk_bf16_f32 v163, v166, v167
	s_nop 0
	global_store_dwordx4 v[168:169], v[160:163], off offset:256 sc1
	s_mov_b64 s[34:35], 0x50000
	v_pk_mul_f32 v[128:129], v[28:29], s[24:25] op_sel_hi:[1,0]
	v_pk_mul_f32 v[130:131], v[30:31], s[24:25] op_sel_hi:[1,0]
	v_pk_mul_f32 v[132:133], v[24:25], s[24:25] op_sel_hi:[1,0]
	v_pk_mul_f32 v[134:135], v[26:27], s[24:25] op_sel_hi:[1,0]
	v_pk_mul_f32 v[160:161], v[20:21], s[24:25] op_sel_hi:[1,0]
	v_pk_mul_f32 v[162:163], v[22:23], s[24:25] op_sel_hi:[1,0]
	v_pk_mul_f32 v[164:165], v[16:17], s[24:25] op_sel_hi:[1,0]
	v_pk_mul_f32 v[166:167], v[18:19], s[24:25] op_sel_hi:[1,0]
	v_exp_f32_e32 v128, v128
	v_exp_f32_e32 v129, v129
	v_exp_f32_e32 v130, v130
	v_exp_f32_e32 v131, v131
	v_exp_f32_e32 v132, v132
	v_exp_f32_e32 v133, v133
	v_exp_f32_e32 v134, v134
	v_exp_f32_e32 v135, v135
	v_exp_f32_e32 v160, v160
	v_exp_f32_e32 v161, v161
	v_exp_f32_e32 v162, v162
	v_exp_f32_e32 v163, v163
	v_exp_f32_e32 v164, v164
	v_exp_f32_e32 v165, v165
	v_exp_f32_e32 v166, v166
	v_exp_f32_e32 v167, v167
	v_lshl_add_u64 v[170:171], v[158:159], 0, s[34:35]
	v_pk_add_f32 v[128:129], v[128:129], 1.0 op_sel_hi:[1,0]
	v_pk_add_f32 v[130:131], v[130:131], 1.0 op_sel_hi:[1,0]
	v_pk_add_f32 v[132:133], v[132:133], 1.0 op_sel_hi:[1,0]
	v_pk_add_f32 v[134:135], v[134:135], 1.0 op_sel_hi:[1,0]
	v_pk_add_f32 v[160:161], v[160:161], 1.0 op_sel_hi:[1,0]
	v_pk_add_f32 v[162:163], v[162:163], 1.0 op_sel_hi:[1,0]
	v_pk_add_f32 v[164:165], v[164:165], 1.0 op_sel_hi:[1,0]
	v_pk_add_f32 v[166:167], v[166:167], 1.0 op_sel_hi:[1,0]
	v_rcp_f32_e32 v128, v128
	v_rcp_f32_e32 v129, v129
	v_rcp_f32_e32 v130, v130
	v_rcp_f32_e32 v131, v131
	v_rcp_f32_e32 v132, v132
	v_rcp_f32_e32 v133, v133
	v_rcp_f32_e32 v134, v134
	v_rcp_f32_e32 v135, v135
	v_rcp_f32_e32 v160, v160
	v_rcp_f32_e32 v161, v161
	v_rcp_f32_e32 v162, v162
	v_rcp_f32_e32 v163, v163
	v_rcp_f32_e32 v164, v164
	v_rcp_f32_e32 v165, v165
	v_rcp_f32_e32 v166, v166
	v_rcp_f32_e32 v167, v167
	v_max_f32_e32 v128, s25, v128
	v_max_f32_e32 v129, s25, v129
	v_max_f32_e32 v130, s25, v130
	v_max_f32_e32 v131, s25, v131
	v_max_f32_e32 v132, s25, v132
	v_max_f32_e32 v133, s25, v133
	v_max_f32_e32 v134, s25, v134
	v_max_f32_e32 v135, s25, v135
	v_max_f32_e32 v160, s25, v160
	v_max_f32_e32 v161, s25, v161
	v_max_f32_e32 v162, s25, v162
	v_max_f32_e32 v163, s25, v163
	v_max_f32_e32 v164, s25, v164
	v_max_f32_e32 v165, s25, v165
	v_max_f32_e32 v166, s25, v166
	v_max_f32_e32 v167, s25, v167
	v_cvt_pk_bf16_f32 v128, v128, v129
	v_cvt_pk_bf16_f32 v129, v130, v131
	v_cvt_pk_bf16_f32 v130, v132, v133
	v_cvt_pk_bf16_f32 v131, v134, v135
	v_cvt_pk_bf16_f32 v160, v160, v161
	global_store_dwordx4 v[170:171], v[128:131], off sc1
	v_cvt_pk_bf16_f32 v161, v162, v163
	v_cvt_pk_bf16_f32 v162, v164, v165
	v_cvt_pk_bf16_f32 v163, v166, v167
	s_nop 0
	global_store_dwordx4 v[170:171], v[160:163], off offset:256 sc1
	s_mov_b64 s[34:35], 0x58000
	v_pk_mul_f32 v[128:129], v[12:13], s[24:25] op_sel_hi:[1,0]
	v_pk_mul_f32 v[130:131], v[14:15], s[24:25] op_sel_hi:[1,0]
	v_pk_mul_f32 v[132:133], v[8:9], s[24:25] op_sel_hi:[1,0]
	v_pk_mul_f32 v[134:135], v[10:11], s[24:25] op_sel_hi:[1,0]
	v_pk_mul_f32 v[160:161], v[4:5], s[24:25] op_sel_hi:[1,0]
	v_pk_mul_f32 v[162:163], v[6:7], s[24:25] op_sel_hi:[1,0]
	v_pk_mul_f32 v[164:165], v[0:1], s[24:25] op_sel_hi:[1,0]
	v_pk_mul_f32 v[166:167], v[2:3], s[24:25] op_sel_hi:[1,0]
	v_exp_f32_e32 v128, v128
	v_exp_f32_e32 v129, v129
	v_exp_f32_e32 v130, v130
	v_exp_f32_e32 v131, v131
	v_exp_f32_e32 v132, v132
	v_exp_f32_e32 v133, v133
	v_exp_f32_e32 v134, v134
	v_exp_f32_e32 v135, v135
	v_exp_f32_e32 v160, v160
	v_exp_f32_e32 v161, v161
	v_exp_f32_e32 v162, v162
	v_exp_f32_e32 v163, v163
	v_exp_f32_e32 v164, v164
	v_exp_f32_e32 v165, v165
	v_exp_f32_e32 v166, v166
	v_exp_f32_e32 v167, v167
	v_lshl_add_u64 v[168:169], v[158:159], 0, s[34:35]
	v_pk_add_f32 v[128:129], v[128:129], 1.0 op_sel_hi:[1,0]
	v_pk_add_f32 v[130:131], v[130:131], 1.0 op_sel_hi:[1,0]
	v_pk_add_f32 v[132:133], v[132:133], 1.0 op_sel_hi:[1,0]
	v_pk_add_f32 v[134:135], v[134:135], 1.0 op_sel_hi:[1,0]
	v_pk_add_f32 v[160:161], v[160:161], 1.0 op_sel_hi:[1,0]
	v_pk_add_f32 v[162:163], v[162:163], 1.0 op_sel_hi:[1,0]
	v_pk_add_f32 v[164:165], v[164:165], 1.0 op_sel_hi:[1,0]
	v_pk_add_f32 v[166:167], v[166:167], 1.0 op_sel_hi:[1,0]
	v_rcp_f32_e32 v128, v128
	v_rcp_f32_e32 v129, v129
	v_rcp_f32_e32 v130, v130
	v_rcp_f32_e32 v131, v131
	v_rcp_f32_e32 v132, v132
	v_rcp_f32_e32 v133, v133
	v_rcp_f32_e32 v134, v134
	v_rcp_f32_e32 v135, v135
	v_rcp_f32_e32 v160, v160
	v_rcp_f32_e32 v161, v161
	v_rcp_f32_e32 v162, v162
	v_rcp_f32_e32 v163, v163
	v_rcp_f32_e32 v164, v164
	v_rcp_f32_e32 v165, v165
	v_rcp_f32_e32 v166, v166
	v_rcp_f32_e32 v167, v167
	v_max_f32_e32 v128, s25, v128
	v_max_f32_e32 v129, s25, v129
	v_max_f32_e32 v130, s25, v130
	v_max_f32_e32 v131, s25, v131
	v_max_f32_e32 v132, s25, v132
	v_max_f32_e32 v133, s25, v133
	v_max_f32_e32 v134, s25, v134
	v_max_f32_e32 v135, s25, v135
	v_max_f32_e32 v160, s25, v160
	v_max_f32_e32 v161, s25, v161
	v_max_f32_e32 v162, s25, v162
	v_max_f32_e32 v163, s25, v163
	v_max_f32_e32 v164, s25, v164
	v_max_f32_e32 v165, s25, v165
	v_max_f32_e32 v166, s25, v166
	v_max_f32_e32 v167, s25, v167
	v_cvt_pk_bf16_f32 v128, v128, v129
	v_cvt_pk_bf16_f32 v129, v130, v131
	v_cvt_pk_bf16_f32 v130, v132, v133
	v_cvt_pk_bf16_f32 v131, v134, v135
	v_cvt_pk_bf16_f32 v160, v160, v161
	global_store_dwordx4 v[168:169], v[128:131], off sc1
	v_cvt_pk_bf16_f32 v161, v162, v163
	v_cvt_pk_bf16_f32 v162, v164, v165
	v_cvt_pk_bf16_f32 v163, v166, v167
	s_nop 0
	global_store_dwordx4 v[168:169], v[160:163], off offset:256 sc1
	s_branch .Lep_done
; #define GAS __attribute__((address_space(1)))
; __device__ __forceinline__ float fsigmoid(float x) { return frcp(1.0f + fexp2(-x * LOG2E)); }
; __device__ __forceinline__ v4u pack8(const f32x4 a, const f32x4 b) { v4u w; w.x = cvt_pk_bf16(a[0], a[1]); w.y = cvt_pk_bf16(a[2], a[3]); w.z = cvt_pk_bf16(b[0], b[1]); w.w = cvt_pk_bf16(b[2], b[3]); return w; }
; #define NT_ST(p, v) __builtin_nontemporal_store((v), (p))
;     __device__ __forceinline__ void operator()(Acc& acc, const Unit& u, int wr, int wc, int fr, int fq, LAS unsigned char* lds) const {
;     ...
;                     for (int j = 0; j < 4; ++j) { const float sa = fsigmoid(a[j]), sb = fsigmoid(b[j]);
;                         a[j] = act == 1 ? a[j] * sa : fmaxf(sa, 1e-30f); b[j] = act == 1 ? b[j] * sb : fmaxf(sb, 1e-30f); } }
;                 NT_ST((GAS v4u*)(dst + (size_t)row * 1024 + cg0 + bj * 128), pack8(a, b)); } }
.Lep_silu:
	v_pk_mul_f32 v[128:129], v[124:125], s[24:25] op_sel_hi:[1,0]
	v_pk_mul_f32 v[130:131], v[126:127], s[24:25] op_sel_hi:[1,0]
	v_pk_mul_f32 v[132:133], v[120:121], s[24:25] op_sel_hi:[1,0]
	v_pk_mul_f32 v[134:135], v[122:123], s[24:25] op_sel_hi:[1,0]
	v_pk_mul_f32 v[160:161], v[116:117], s[24:25] op_sel_hi:[1,0]
	v_pk_mul_f32 v[162:163], v[118:119], s[24:25] op_sel_hi:[1,0]
	v_pk_mul_f32 v[164:165], v[112:113], s[24:25] op_sel_hi:[1,0]
	v_pk_mul_f32 v[166:167], v[114:115], s[24:25] op_sel_hi:[1,0]
	v_exp_f32_e32 v128, v128
	v_exp_f32_e32 v129, v129
	v_exp_f32_e32 v130, v130
	v_exp_f32_e32 v131, v131
	v_exp_f32_e32 v132, v132
	v_exp_f32_e32 v133, v133
	v_exp_f32_e32 v134, v134
	v_exp_f32_e32 v135, v135
	v_exp_f32_e32 v160, v160
	v_exp_f32_e32 v161, v161
	v_exp_f32_e32 v162, v162
	v_exp_f32_e32 v163, v163
	v_exp_f32_e32 v164, v164
	v_exp_f32_e32 v165, v165
	v_exp_f32_e32 v166, v166
	v_exp_f32_e32 v167, v167
	v_pk_add_f32 v[128:129], v[128:129], 1.0 op_sel_hi:[1,0]
	v_pk_add_f32 v[130:131], v[130:131], 1.0 op_sel_hi:[1,0]
	v_pk_add_f32 v[132:133], v[132:133], 1.0 op_sel_hi:[1,0]
	v_pk_add_f32 v[134:135], v[134:135], 1.0 op_sel_hi:[1,0]
	v_pk_add_f32 v[160:161], v[160:161], 1.0 op_sel_hi:[1,0]
	v_pk_add_f32 v[162:163], v[162:163], 1.0 op_sel_hi:[1,0]
	v_pk_add_f32 v[164:165], v[164:165], 1.0 op_sel_hi:[1,0]
	v_pk_add_f32 v[166:167], v[166:167], 1.0 op_sel_hi:[1,0]
	v_rcp_f32_e32 v128, v128
	v_rcp_f32_e32 v129, v129
	v_rcp_f32_e32 v130, v130
	v_rcp_f32_e32 v131, v131
	v_rcp_f32_e32 v132, v132
	v_rcp_f32_e32 v133, v133
	v_rcp_f32_e32 v134, v134
	v_rcp_f32_e32 v135, v135
	v_rcp_f32_e32 v160, v160
	v_rcp_f32_e32 v161, v161
	v_rcp_f32_e32 v162, v162
	v_rcp_f32_e32 v163, v163
	v_rcp_f32_e32 v164, v164
	v_rcp_f32_e32 v165, v165
	v_rcp_f32_e32 v166, v166
	v_rcp_f32_e32 v167, v167
	v_pk_mul_f32 v[128:129], v[124:125], v[128:129]
	v_pk_mul_f32 v[130:131], v[126:127], v[130:131]
	v_pk_mul_f32 v[132:133], v[120:121], v[132:133]
	v_pk_mul_f32 v[134:135], v[122:123], v[134:135]
	v_pk_mul_f32 v[160:161], v[116:117], v[160:161]
	v_pk_mul_f32 v[162:163], v[118:119], v[162:163]
	v_pk_mul_f32 v[164:165], v[112:113], v[164:165]
	v_pk_mul_f32 v[166:167], v[114:115], v[166:167]
	v_cvt_pk_bf16_f32 v128, v128, v129
	v_cvt_pk_bf16_f32 v129, v130, v131
	v_cvt_pk_bf16_f32 v130, v132, v133
	v_cvt_pk_bf16_f32 v131, v134, v135
	v_cvt_pk_bf16_f32 v160, v160, v161
	global_store_dwordx4 v[158:159], v[128:131], off sc1
	v_cvt_pk_bf16_f32 v161, v162, v163
	v_cvt_pk_bf16_f32 v162, v164, v165
	v_cvt_pk_bf16_f32 v163, v166, v167
	s_nop 0
	global_store_dwordx4 v[158:159], v[160:163], off offset:256 sc1
	s_mov_b64 s[34:35], 0x8000
	v_pk_mul_f32 v[128:129], v[108:109], s[24:25] op_sel_hi:[1,0]
	v_pk_mul_f32 v[130:131], v[110:111], s[24:25] op_sel_hi:[1,0]
	v_pk_mul_f32 v[132:133], v[104:105], s[24:25] op_sel_hi:[1,0]
	v_pk_mul_f32 v[134:135], v[106:107], s[24:25] op_sel_hi:[1,0]
	v_pk_mul_f32 v[160:161], v[100:101], s[24:25] op_sel_hi:[1,0]
	v_pk_mul_f32 v[162:163], v[102:103], s[24:25] op_sel_hi:[1,0]
	v_pk_mul_f32 v[164:165], v[96:97], s[24:25] op_sel_hi:[1,0]
	v_pk_mul_f32 v[166:167], v[98:99], s[24:25] op_sel_hi:[1,0]
	v_exp_f32_e32 v128, v128
	v_exp_f32_e32 v129, v129
	v_exp_f32_e32 v130, v130
	v_exp_f32_e32 v131, v131
	v_exp_f32_e32 v132, v132
	v_exp_f32_e32 v133, v133
	v_exp_f32_e32 v134, v134
	v_exp_f32_e32 v135, v135
	v_exp_f32_e32 v160, v160
	v_exp_f32_e32 v161, v161
	v_exp_f32_e32 v162, v162
	v_exp_f32_e32 v163, v163
	v_exp_f32_e32 v164, v164
	v_exp_f32_e32 v165, v165
	v_exp_f32_e32 v166, v166
	v_exp_f32_e32 v167, v167
	v_lshl_add_u64 v[168:169], v[158:159], 0, s[34:35]
	v_pk_add_f32 v[128:129], v[128:129], 1.0 op_sel_hi:[1,0]
	v_pk_add_f32 v[130:131], v[130:131], 1.0 op_sel_hi:[1,0]
	v_pk_add_f32 v[132:133], v[132:133], 1.0 op_sel_hi:[1,0]
	v_pk_add_f32 v[134:135], v[134:135], 1.0 op_sel_hi:[1,0]
	v_pk_add_f32 v[160:161], v[160:161], 1.0 op_sel_hi:[1,0]
	v_pk_add_f32 v[162:163], v[162:163], 1.0 op_sel_hi:[1,0]
	v_pk_add_f32 v[164:165], v[164:165], 1.0 op_sel_hi:[1,0]
	v_pk_add_f32 v[166:167], v[166:167], 1.0 op_sel_hi:[1,0]
	v_rcp_f32_e32 v128, v128
	v_rcp_f32_e32 v129, v129
	v_rcp_f32_e32 v130, v130
	v_rcp_f32_e32 v131, v131
	v_rcp_f32_e32 v132, v132
	v_rcp_f32_e32 v133, v133
	v_rcp_f32_e32 v134, v134
	v_rcp_f32_e32 v135, v135
	v_rcp_f32_e32 v160, v160
	v_rcp_f32_e32 v161, v161
	v_rcp_f32_e32 v162, v162
	v_rcp_f32_e32 v163, v163
	v_rcp_f32_e32 v164, v164
	v_rcp_f32_e32 v165, v165
	v_rcp_f32_e32 v166, v166
	v_rcp_f32_e32 v167, v167
	v_pk_mul_f32 v[128:129], v[108:109], v[128:129]
	v_pk_mul_f32 v[130:131], v[110:111], v[130:131]
	v_pk_mul_f32 v[132:133], v[104:105], v[132:133]
	v_pk_mul_f32 v[134:135], v[106:107], v[134:135]
	v_pk_mul_f32 v[160:161], v[100:101], v[160:161]
	v_pk_mul_f32 v[162:163], v[102:103], v[162:163]
	v_pk_mul_f32 v[164:165], v[96:97], v[164:165]
	v_pk_mul_f32 v[166:167], v[98:99], v[166:167]
	v_cvt_pk_bf16_f32 v128, v128, v129
	v_cvt_pk_bf16_f32 v129, v130, v131
	v_cvt_pk_bf16_f32 v130, v132, v133
	v_cvt_pk_bf16_f32 v131, v134, v135
	v_cvt_pk_bf16_f32 v160, v160, v161
	global_store_dwordx4 v[168:169], v[128:131], off sc1
	v_cvt_pk_bf16_f32 v161, v162, v163
	v_cvt_pk_bf16_f32 v162, v164, v165
	v_cvt_pk_bf16_f32 v163, v166, v167
	s_nop 0
	global_store_dwordx4 v[168:169], v[160:163], off offset:256 sc1
	s_mov_b64 s[34:35], 0x10000
	v_pk_mul_f32 v[128:129], v[92:93], s[24:25] op_sel_hi:[1,0]
	v_pk_mul_f32 v[130:131], v[94:95], s[24:25] op_sel_hi:[1,0]
	v_pk_mul_f32 v[132:133], v[88:89], s[24:25] op_sel_hi:[1,0]
	v_pk_mul_f32 v[134:135], v[90:91], s[24:25] op_sel_hi:[1,0]
	v_pk_mul_f32 v[160:161], v[84:85], s[24:25] op_sel_hi:[1,0]
; #define GAS __attribute__((address_space(1)))
; __device__ __forceinline__ float fsigmoid(float x) { return frcp(1.0f + fexp2(-x * LOG2E)); }
; __device__ __forceinline__ v4u pack8(const f32x4 a, const f32x4 b) { v4u w; w.x = cvt_pk_bf16(a[0], a[1]); w.y = cvt_pk_bf16(a[2], a[3]); w.z = cvt_pk_bf16(b[0], b[1]); w.w = cvt_pk_bf16(b[2], b[3]); return w; }
; #define NT_ST(p, v) __builtin_nontemporal_store((v), (p))
;     __device__ __forceinline__ void operator()(Acc& acc, const Unit& u, int wr, int wc, int fr, int fq, LAS unsigned char* lds) const {
;     ...
;                     for (int j = 0; j < 4; ++j) { const float sa = fsigmoid(a[j]), sb = fsigmoid(b[j]);
;                         a[j] = act == 1 ? a[j] * sa : fmaxf(sa, 1e-30f); b[j] = act == 1 ? b[j] * sb : fmaxf(sb, 1e-30f); } }
;                 NT_ST((GAS v4u*)(dst + (size_t)row * 1024 + cg0 + bj * 128), pack8(a, b)); } }
	v_pk_mul_f32 v[162:163], v[86:87], s[24:25] op_sel_hi:[1,0]
	v_pk_mul_f32 v[164:165], v[80:81], s[24:25] op_sel_hi:[1,0]
	v_pk_mul_f32 v[166:167], v[82:83], s[24:25] op_sel_hi:[1,0]
	v_exp_f32_e32 v128, v128
	v_exp_f32_e32 v129, v129
	v_exp_f32_e32 v130, v130
	v_exp_f32_e32 v131, v131
	v_exp_f32_e32 v132, v132
	v_exp_f32_e32 v133, v133
	v_exp_f32_e32 v134, v134
	v_exp_f32_e32 v135, v135
	v_exp_f32_e32 v160, v160
	v_exp_f32_e32 v161, v161
	v_exp_f32_e32 v162, v162
	v_exp_f32_e32 v163, v163
	v_exp_f32_e32 v164, v164
	v_exp_f32_e32 v165, v165
	v_exp_f32_e32 v166, v166
	v_exp_f32_e32 v167, v167
	v_lshl_add_u64 v[170:171], v[158:159], 0, s[34:35]
	v_pk_add_f32 v[128:129], v[128:129], 1.0 op_sel_hi:[1,0]
	v_pk_add_f32 v[130:131], v[130:131], 1.0 op_sel_hi:[1,0]
	v_pk_add_f32 v[132:133], v[132:133], 1.0 op_sel_hi:[1,0]
	v_pk_add_f32 v[134:135], v[134:135], 1.0 op_sel_hi:[1,0]
	v_pk_add_f32 v[160:161], v[160:161], 1.0 op_sel_hi:[1,0]
	v_pk_add_f32 v[162:163], v[162:163], 1.0 op_sel_hi:[1,0]
	v_pk_add_f32 v[164:165], v[164:165], 1.0 op_sel_hi:[1,0]
	v_pk_add_f32 v[166:167], v[166:167], 1.0 op_sel_hi:[1,0]
	v_rcp_f32_e32 v128, v128
	v_rcp_f32_e32 v129, v129
	v_rcp_f32_e32 v130, v130
	v_rcp_f32_e32 v131, v131
	v_rcp_f32_e32 v132, v132
	v_rcp_f32_e32 v133, v133
	v_rcp_f32_e32 v134, v134
	v_rcp_f32_e32 v135, v135
	v_rcp_f32_e32 v160, v160
	v_rcp_f32_e32 v161, v161
	v_rcp_f32_e32 v162, v162
	v_rcp_f32_e32 v163, v163
	v_rcp_f32_e32 v164, v164
	v_rcp_f32_e32 v165, v165
	v_rcp_f32_e32 v166, v166
	v_rcp_f32_e32 v167, v167
	v_pk_mul_f32 v[128:129], v[92:93], v[128:129]
	v_pk_mul_f32 v[130:131], v[94:95], v[130:131]
	v_pk_mul_f32 v[132:133], v[88:89], v[132:133]
	v_pk_mul_f32 v[134:135], v[90:91], v[134:135]
	v_pk_mul_f32 v[160:161], v[84:85], v[160:161]
	v_pk_mul_f32 v[162:163], v[86:87], v[162:163]
	v_pk_mul_f32 v[164:165], v[80:81], v[164:165]
	v_pk_mul_f32 v[166:167], v[82:83], v[166:167]
	v_cvt_pk_bf16_f32 v128, v128, v129
	v_cvt_pk_bf16_f32 v129, v130, v131
	v_cvt_pk_bf16_f32 v130, v132, v133
	v_cvt_pk_bf16_f32 v131, v134, v135
	v_cvt_pk_bf16_f32 v160, v160, v161
	global_store_dwordx4 v[170:171], v[128:131], off sc1
	v_cvt_pk_bf16_f32 v161, v162, v163
	v_cvt_pk_bf16_f32 v162, v164, v165
	v_cvt_pk_bf16_f32 v163, v166, v167
	s_nop 0
	global_store_dwordx4 v[170:171], v[160:163], off offset:256 sc1
	s_mov_b64 s[34:35], 0x18000
	v_pk_mul_f32 v[128:129], v[76:77], s[24:25] op_sel_hi:[1,0]
	v_pk_mul_f32 v[130:131], v[78:79], s[24:25] op_sel_hi:[1,0]
	v_pk_mul_f32 v[132:133], v[72:73], s[24:25] op_sel_hi:[1,0]
	v_pk_mul_f32 v[134:135], v[74:75], s[24:25] op_sel_hi:[1,0]
	v_pk_mul_f32 v[160:161], v[68:69], s[24:25] op_sel_hi:[1,0]
	v_pk_mul_f32 v[162:163], v[70:71], s[24:25] op_sel_hi:[1,0]
	v_pk_mul_f32 v[164:165], v[64:65], s[24:25] op_sel_hi:[1,0]
	v_pk_mul_f32 v[166:167], v[66:67], s[24:25] op_sel_hi:[1,0]
	v_exp_f32_e32 v128, v128
	v_exp_f32_e32 v129, v129
	v_exp_f32_e32 v130, v130
	v_exp_f32_e32 v131, v131
	v_exp_f32_e32 v132, v132
	v_exp_f32_e32 v133, v133
	v_exp_f32_e32 v134, v134
	v_exp_f32_e32 v135, v135
	v_exp_f32_e32 v160, v160
	v_exp_f32_e32 v161, v161
	v_exp_f32_e32 v162, v162
	v_exp_f32_e32 v163, v163
	v_exp_f32_e32 v164, v164
	v_exp_f32_e32 v165, v165
	v_exp_f32_e32 v166, v166
	v_exp_f32_e32 v167, v167
	v_lshl_add_u64 v[168:169], v[158:159], 0, s[34:35]
	v_pk_add_f32 v[128:129], v[128:129], 1.0 op_sel_hi:[1,0]
	v_pk_add_f32 v[130:131], v[130:131], 1.0 op_sel_hi:[1,0]
	v_pk_add_f32 v[132:133], v[132:133], 1.0 op_sel_hi:[1,0]
	v_pk_add_f32 v[134:135], v[134:135], 1.0 op_sel_hi:[1,0]
	v_pk_add_f32 v[160:161], v[160:161], 1.0 op_sel_hi:[1,0]
	v_pk_add_f32 v[162:163], v[162:163], 1.0 op_sel_hi:[1,0]
	v_pk_add_f32 v[164:165], v[164:165], 1.0 op_sel_hi:[1,0]
	v_pk_add_f32 v[166:167], v[166:167], 1.0 op_sel_hi:[1,0]
	v_rcp_f32_e32 v128, v128
	v_rcp_f32_e32 v129, v129
	v_rcp_f32_e32 v130, v130
	v_rcp_f32_e32 v131, v131
	v_rcp_f32_e32 v132, v132
	v_rcp_f32_e32 v133, v133
	v_rcp_f32_e32 v134, v134
	v_rcp_f32_e32 v135, v135
	v_rcp_f32_e32 v160, v160
	v_rcp_f32_e32 v161, v161
	v_rcp_f32_e32 v162, v162
	v_rcp_f32_e32 v163, v163
	v_rcp_f32_e32 v164, v164
	v_rcp_f32_e32 v165, v165
	v_rcp_f32_e32 v166, v166
	v_rcp_f32_e32 v167, v167
	v_pk_mul_f32 v[128:129], v[76:77], v[128:129]
	v_pk_mul_f32 v[130:131], v[78:79], v[130:131]
	v_pk_mul_f32 v[132:133], v[72:73], v[132:133]
	v_pk_mul_f32 v[134:135], v[74:75], v[134:135]
	v_pk_mul_f32 v[160:161], v[68:69], v[160:161]
	v_pk_mul_f32 v[162:163], v[70:71], v[162:163]
	v_pk_mul_f32 v[164:165], v[64:65], v[164:165]
	v_pk_mul_f32 v[166:167], v[66:67], v[166:167]
	v_cvt_pk_bf16_f32 v128, v128, v129
	v_cvt_pk_bf16_f32 v129, v130, v131
	v_cvt_pk_bf16_f32 v130, v132, v133
	v_cvt_pk_bf16_f32 v131, v134, v135
	v_cvt_pk_bf16_f32 v160, v160, v161
	global_store_dwordx4 v[168:169], v[128:131], off sc1
	v_cvt_pk_bf16_f32 v161, v162, v163
	v_cvt_pk_bf16_f32 v162, v164, v165
	v_cvt_pk_bf16_f32 v163, v166, v167
	s_nop 0
	global_store_dwordx4 v[168:169], v[160:163], off offset:256 sc1
	s_mov_b64 s[34:35], 0x40000
	v_pk_mul_f32 v[128:129], v[60:61], s[24:25] op_sel_hi:[1,0]
	v_pk_mul_f32 v[130:131], v[62:63], s[24:25] op_sel_hi:[1,0]
	v_pk_mul_f32 v[132:133], v[56:57], s[24:25] op_sel_hi:[1,0]
	v_pk_mul_f32 v[134:135], v[58:59], s[24:25] op_sel_hi:[1,0]
	v_pk_mul_f32 v[160:161], v[52:53], s[24:25] op_sel_hi:[1,0]
	v_pk_mul_f32 v[162:163], v[54:55], s[24:25] op_sel_hi:[1,0]
	v_pk_mul_f32 v[164:165], v[48:49], s[24:25] op_sel_hi:[1,0]
	v_pk_mul_f32 v[166:167], v[50:51], s[24:25] op_sel_hi:[1,0]
	v_exp_f32_e32 v128, v128
	v_exp_f32_e32 v129, v129
	v_exp_f32_e32 v130, v130
	v_exp_f32_e32 v131, v131
	v_exp_f32_e32 v132, v132
; #define GAS __attribute__((address_space(1)))
; __device__ __forceinline__ float fsigmoid(float x) { return frcp(1.0f + fexp2(-x * LOG2E)); }
; __device__ __forceinline__ v4u pack8(const f32x4 a, const f32x4 b) { v4u w; w.x = cvt_pk_bf16(a[0], a[1]); w.y = cvt_pk_bf16(a[2], a[3]); w.z = cvt_pk_bf16(b[0], b[1]); w.w = cvt_pk_bf16(b[2], b[3]); return w; }
; #define NT_ST(p, v) __builtin_nontemporal_store((v), (p))
;     __device__ __forceinline__ void operator()(Acc& acc, const Unit& u, int wr, int wc, int fr, int fq, LAS unsigned char* lds) const {
;     ...
;                     for (int j = 0; j < 4; ++j) { const float sa = fsigmoid(a[j]), sb = fsigmoid(b[j]);
;                         a[j] = act == 1 ? a[j] * sa : fmaxf(sa, 1e-30f); b[j] = act == 1 ? b[j] * sb : fmaxf(sb, 1e-30f); } }
;                 NT_ST((GAS v4u*)(dst + (size_t)row * 1024 + cg0 + bj * 128), pack8(a, b)); } }
	v_exp_f32_e32 v133, v133
	v_exp_f32_e32 v134, v134
	v_exp_f32_e32 v135, v135
	v_exp_f32_e32 v160, v160
	v_exp_f32_e32 v161, v161
	v_exp_f32_e32 v162, v162
	v_exp_f32_e32 v163, v163
	v_exp_f32_e32 v164, v164
	v_exp_f32_e32 v165, v165
	v_exp_f32_e32 v166, v166
	v_exp_f32_e32 v167, v167
	v_lshl_add_u64 v[170:171], v[158:159], 0, s[34:35]
	v_pk_add_f32 v[128:129], v[128:129], 1.0 op_sel_hi:[1,0]
	v_pk_add_f32 v[130:131], v[130:131], 1.0 op_sel_hi:[1,0]
	v_pk_add_f32 v[132:133], v[132:133], 1.0 op_sel_hi:[1,0]
	v_pk_add_f32 v[134:135], v[134:135], 1.0 op_sel_hi:[1,0]
	v_pk_add_f32 v[160:161], v[160:161], 1.0 op_sel_hi:[1,0]
	v_pk_add_f32 v[162:163], v[162:163], 1.0 op_sel_hi:[1,0]
	v_pk_add_f32 v[164:165], v[164:165], 1.0 op_sel_hi:[1,0]
	v_pk_add_f32 v[166:167], v[166:167], 1.0 op_sel_hi:[1,0]
	v_rcp_f32_e32 v128, v128
	v_rcp_f32_e32 v129, v129
	v_rcp_f32_e32 v130, v130
	v_rcp_f32_e32 v131, v131
	v_rcp_f32_e32 v132, v132
	v_rcp_f32_e32 v133, v133
	v_rcp_f32_e32 v134, v134
	v_rcp_f32_e32 v135, v135
	v_rcp_f32_e32 v160, v160
	v_rcp_f32_e32 v161, v161
	v_rcp_f32_e32 v162, v162
	v_rcp_f32_e32 v163, v163
	v_rcp_f32_e32 v164, v164
	v_rcp_f32_e32 v165, v165
	v_rcp_f32_e32 v166, v166
	v_rcp_f32_e32 v167, v167
	v_pk_mul_f32 v[128:129], v[60:61], v[128:129]
	v_pk_mul_f32 v[130:131], v[62:63], v[130:131]
	v_pk_mul_f32 v[132:133], v[56:57], v[132:133]
	v_pk_mul_f32 v[134:135], v[58:59], v[134:135]
	v_pk_mul_f32 v[160:161], v[52:53], v[160:161]
	v_pk_mul_f32 v[162:163], v[54:55], v[162:163]
	v_pk_mul_f32 v[164:165], v[48:49], v[164:165]
	v_pk_mul_f32 v[166:167], v[50:51], v[166:167]
	v_cvt_pk_bf16_f32 v128, v128, v129
	v_cvt_pk_bf16_f32 v129, v130, v131
	v_cvt_pk_bf16_f32 v130, v132, v133
	v_cvt_pk_bf16_f32 v131, v134, v135
	v_cvt_pk_bf16_f32 v160, v160, v161
	global_store_dwordx4 v[170:171], v[128:131], off sc1
	v_cvt_pk_bf16_f32 v161, v162, v163
	v_cvt_pk_bf16_f32 v162, v164, v165
	v_cvt_pk_bf16_f32 v163, v166, v167
	s_nop 0
	global_store_dwordx4 v[170:171], v[160:163], off offset:256 sc1
	s_mov_b64 s[34:35], 0x48000
	v_pk_mul_f32 v[128:129], v[44:45], s[24:25] op_sel_hi:[1,0]
	v_pk_mul_f32 v[130:131], v[46:47], s[24:25] op_sel_hi:[1,0]
	v_pk_mul_f32 v[132:133], v[40:41], s[24:25] op_sel_hi:[1,0]
	v_pk_mul_f32 v[134:135], v[42:43], s[24:25] op_sel_hi:[1,0]
	v_pk_mul_f32 v[160:161], v[36:37], s[24:25] op_sel_hi:[1,0]
	v_pk_mul_f32 v[162:163], v[38:39], s[24:25] op_sel_hi:[1,0]
	v_pk_mul_f32 v[164:165], v[32:33], s[24:25] op_sel_hi:[1,0]
	v_pk_mul_f32 v[166:167], v[34:35], s[24:25] op_sel_hi:[1,0]
	v_exp_f32_e32 v128, v128
	v_exp_f32_e32 v129, v129
	v_exp_f32_e32 v130, v130
	v_exp_f32_e32 v131, v131
	v_exp_f32_e32 v132, v132
	v_exp_f32_e32 v133, v133
	v_exp_f32_e32 v134, v134
	v_exp_f32_e32 v135, v135
	v_exp_f32_e32 v160, v160
	v_exp_f32_e32 v161, v161
	v_exp_f32_e32 v162, v162
	v_exp_f32_e32 v163, v163
	v_exp_f32_e32 v164, v164
	v_exp_f32_e32 v165, v165
	v_exp_f32_e32 v166, v166
	v_exp_f32_e32 v167, v167
	v_lshl_add_u64 v[168:169], v[158:159], 0, s[34:35]
	v_pk_add_f32 v[128:129], v[128:129], 1.0 op_sel_hi:[1,0]
	v_pk_add_f32 v[130:131], v[130:131], 1.0 op_sel_hi:[1,0]
	v_pk_add_f32 v[132:133], v[132:133], 1.0 op_sel_hi:[1,0]
	v_pk_add_f32 v[134:135], v[134:135], 1.0 op_sel_hi:[1,0]
	v_pk_add_f32 v[160:161], v[160:161], 1.0 op_sel_hi:[1,0]
	v_pk_add_f32 v[162:163], v[162:163], 1.0 op_sel_hi:[1,0]
	v_pk_add_f32 v[164:165], v[164:165], 1.0 op_sel_hi:[1,0]
	v_pk_add_f32 v[166:167], v[166:167], 1.0 op_sel_hi:[1,0]
	v_rcp_f32_e32 v128, v128
	v_rcp_f32_e32 v129, v129
	v_rcp_f32_e32 v130, v130
	v_rcp_f32_e32 v131, v131
	v_rcp_f32_e32 v132, v132
	v_rcp_f32_e32 v133, v133
	v_rcp_f32_e32 v134, v134
	v_rcp_f32_e32 v135, v135
	v_rcp_f32_e32 v160, v160
	v_rcp_f32_e32 v161, v161
	v_rcp_f32_e32 v162, v162
	v_rcp_f32_e32 v163, v163
	v_rcp_f32_e32 v164, v164
	v_rcp_f32_e32 v165, v165
	v_rcp_f32_e32 v166, v166
	v_rcp_f32_e32 v167, v167
	v_pk_mul_f32 v[128:129], v[44:45], v[128:129]
	v_pk_mul_f32 v[130:131], v[46:47], v[130:131]
	v_pk_mul_f32 v[132:133], v[40:41], v[132:133]
	v_pk_mul_f32 v[134:135], v[42:43], v[134:135]
	v_pk_mul_f32 v[160:161], v[36:37], v[160:161]
	v_pk_mul_f32 v[162:163], v[38:39], v[162:163]
	v_pk_mul_f32 v[164:165], v[32:33], v[164:165]
	v_pk_mul_f32 v[166:167], v[34:35], v[166:167]
	v_cvt_pk_bf16_f32 v128, v128, v129
	v_cvt_pk_bf16_f32 v129, v130, v131
	v_cvt_pk_bf16_f32 v130, v132, v133
	v_cvt_pk_bf16_f32 v131, v134, v135
	v_cvt_pk_bf16_f32 v160, v160, v161
	global_store_dwordx4 v[168:169], v[128:131], off sc1
	v_cvt_pk_bf16_f32 v161, v162, v163
	v_cvt_pk_bf16_f32 v162, v164, v165
	v_cvt_pk_bf16_f32 v163, v166, v167
	s_nop 0
	global_store_dwordx4 v[168:169], v[160:163], off offset:256 sc1
	s_mov_b64 s[34:35], 0x50000
	v_pk_mul_f32 v[128:129], v[28:29], s[24:25] op_sel_hi:[1,0]
	v_pk_mul_f32 v[130:131], v[30:31], s[24:25] op_sel_hi:[1,0]
	v_pk_mul_f32 v[132:133], v[24:25], s[24:25] op_sel_hi:[1,0]
	v_pk_mul_f32 v[134:135], v[26:27], s[24:25] op_sel_hi:[1,0]
	v_pk_mul_f32 v[160:161], v[20:21], s[24:25] op_sel_hi:[1,0]
	v_pk_mul_f32 v[162:163], v[22:23], s[24:25] op_sel_hi:[1,0]
	v_pk_mul_f32 v[164:165], v[16:17], s[24:25] op_sel_hi:[1,0]
	v_pk_mul_f32 v[166:167], v[18:19], s[24:25] op_sel_hi:[1,0]
	v_exp_f32_e32 v128, v128
	v_exp_f32_e32 v129, v129
	v_exp_f32_e32 v130, v130
	v_exp_f32_e32 v131, v131
	v_exp_f32_e32 v132, v132
	v_exp_f32_e32 v133, v133
	v_exp_f32_e32 v134, v134
	v_exp_f32_e32 v135, v135
	v_exp_f32_e32 v160, v160
	v_exp_f32_e32 v161, v161
	v_exp_f32_e32 v162, v162
	v_exp_f32_e32 v163, v163
	v_exp_f32_e32 v164, v164
	v_exp_f32_e32 v165, v165
	v_exp_f32_e32 v166, v166
	v_exp_f32_e32 v167, v167
	v_lshl_add_u64 v[170:171], v[158:159], 0, s[34:35]
; #define GAS __attribute__((address_space(1)))
; __device__ __forceinline__ float fsigmoid(float x) { return frcp(1.0f + fexp2(-x * LOG2E)); }
; __device__ __forceinline__ v4u pack8(const f32x4 a, const f32x4 b) { v4u w; w.x = cvt_pk_bf16(a[0], a[1]); w.y = cvt_pk_bf16(a[2], a[3]); w.z = cvt_pk_bf16(b[0], b[1]); w.w = cvt_pk_bf16(b[2], b[3]); return w; }
; #define NT_ST(p, v) __builtin_nontemporal_store((v), (p))
;     __device__ __forceinline__ void operator()(Acc& acc, const Unit& u, int wr, int wc, int fr, int fq, LAS unsigned char* lds) const {
;     ...
;                     for (int j = 0; j < 4; ++j) { const float sa = fsigmoid(a[j]), sb = fsigmoid(b[j]);
;                         a[j] = act == 1 ? a[j] * sa : fmaxf(sa, 1e-30f); b[j] = act == 1 ? b[j] * sb : fmaxf(sb, 1e-30f); } }
;                 NT_ST((GAS v4u*)(dst + (size_t)row * 1024 + cg0 + bj * 128), pack8(a, b)); } }
	v_pk_add_f32 v[128:129], v[128:129], 1.0 op_sel_hi:[1,0]
	v_pk_add_f32 v[130:131], v[130:131], 1.0 op_sel_hi:[1,0]
	v_pk_add_f32 v[132:133], v[132:133], 1.0 op_sel_hi:[1,0]
	v_pk_add_f32 v[134:135], v[134:135], 1.0 op_sel_hi:[1,0]
	v_pk_add_f32 v[160:161], v[160:161], 1.0 op_sel_hi:[1,0]
	v_pk_add_f32 v[162:163], v[162:163], 1.0 op_sel_hi:[1,0]
	v_pk_add_f32 v[164:165], v[164:165], 1.0 op_sel_hi:[1,0]
	v_pk_add_f32 v[166:167], v[166:167], 1.0 op_sel_hi:[1,0]
	v_rcp_f32_e32 v128, v128
	v_rcp_f32_e32 v129, v129
	v_rcp_f32_e32 v130, v130
	v_rcp_f32_e32 v131, v131
	v_rcp_f32_e32 v132, v132
	v_rcp_f32_e32 v133, v133
	v_rcp_f32_e32 v134, v134
	v_rcp_f32_e32 v135, v135
	v_rcp_f32_e32 v160, v160
	v_rcp_f32_e32 v161, v161
	v_rcp_f32_e32 v162, v162
	v_rcp_f32_e32 v163, v163
	v_rcp_f32_e32 v164, v164
	v_rcp_f32_e32 v165, v165
	v_rcp_f32_e32 v166, v166
	v_rcp_f32_e32 v167, v167
	v_pk_mul_f32 v[128:129], v[28:29], v[128:129]
	v_pk_mul_f32 v[130:131], v[30:31], v[130:131]
	v_pk_mul_f32 v[132:133], v[24:25], v[132:133]
	v_pk_mul_f32 v[134:135], v[26:27], v[134:135]
	v_pk_mul_f32 v[160:161], v[20:21], v[160:161]
	v_pk_mul_f32 v[162:163], v[22:23], v[162:163]
	v_pk_mul_f32 v[164:165], v[16:17], v[164:165]
	v_pk_mul_f32 v[166:167], v[18:19], v[166:167]
	v_cvt_pk_bf16_f32 v128, v128, v129
	v_cvt_pk_bf16_f32 v129, v130, v131
	v_cvt_pk_bf16_f32 v130, v132, v133
	v_cvt_pk_bf16_f32 v131, v134, v135
	v_cvt_pk_bf16_f32 v160, v160, v161
	global_store_dwordx4 v[170:171], v[128:131], off sc1
	v_cvt_pk_bf16_f32 v161, v162, v163
	v_cvt_pk_bf16_f32 v162, v164, v165
	v_cvt_pk_bf16_f32 v163, v166, v167
	s_nop 0
	global_store_dwordx4 v[170:171], v[160:163], off offset:256 sc1
	s_mov_b64 s[34:35], 0x58000
	v_pk_mul_f32 v[128:129], v[12:13], s[24:25] op_sel_hi:[1,0]
	v_pk_mul_f32 v[130:131], v[14:15], s[24:25] op_sel_hi:[1,0]
	v_pk_mul_f32 v[132:133], v[8:9], s[24:25] op_sel_hi:[1,0]
	v_pk_mul_f32 v[134:135], v[10:11], s[24:25] op_sel_hi:[1,0]
	v_pk_mul_f32 v[160:161], v[4:5], s[24:25] op_sel_hi:[1,0]
	v_pk_mul_f32 v[162:163], v[6:7], s[24:25] op_sel_hi:[1,0]
	v_pk_mul_f32 v[164:165], v[0:1], s[24:25] op_sel_hi:[1,0]
	v_pk_mul_f32 v[166:167], v[2:3], s[24:25] op_sel_hi:[1,0]
	v_exp_f32_e32 v128, v128
	v_exp_f32_e32 v129, v129
	v_exp_f32_e32 v130, v130
	v_exp_f32_e32 v131, v131
	v_exp_f32_e32 v132, v132
	v_exp_f32_e32 v133, v133
	v_exp_f32_e32 v134, v134
	v_exp_f32_e32 v135, v135
	v_exp_f32_e32 v160, v160
	v_exp_f32_e32 v161, v161
	v_exp_f32_e32 v162, v162
	v_exp_f32_e32 v163, v163
	v_exp_f32_e32 v164, v164
	v_exp_f32_e32 v165, v165
	v_exp_f32_e32 v166, v166
	v_exp_f32_e32 v167, v167
	v_lshl_add_u64 v[168:169], v[158:159], 0, s[34:35]
	v_pk_add_f32 v[128:129], v[128:129], 1.0 op_sel_hi:[1,0]
	v_pk_add_f32 v[130:131], v[130:131], 1.0 op_sel_hi:[1,0]
	v_pk_add_f32 v[132:133], v[132:133], 1.0 op_sel_hi:[1,0]
	v_pk_add_f32 v[134:135], v[134:135], 1.0 op_sel_hi:[1,0]
	v_pk_add_f32 v[160:161], v[160:161], 1.0 op_sel_hi:[1,0]
	v_pk_add_f32 v[162:163], v[162:163], 1.0 op_sel_hi:[1,0]
	v_pk_add_f32 v[164:165], v[164:165], 1.0 op_sel_hi:[1,0]
	v_pk_add_f32 v[166:167], v[166:167], 1.0 op_sel_hi:[1,0]
	v_rcp_f32_e32 v128, v128
	v_rcp_f32_e32 v129, v129
	v_rcp_f32_e32 v130, v130
	v_rcp_f32_e32 v131, v131
	v_rcp_f32_e32 v132, v132
	v_rcp_f32_e32 v133, v133
	v_rcp_f32_e32 v134, v134
	v_rcp_f32_e32 v135, v135
	v_rcp_f32_e32 v160, v160
	v_rcp_f32_e32 v161, v161
	v_rcp_f32_e32 v162, v162
	v_rcp_f32_e32 v163, v163
	v_rcp_f32_e32 v164, v164
	v_rcp_f32_e32 v165, v165
	v_rcp_f32_e32 v166, v166
	v_rcp_f32_e32 v167, v167
	v_pk_mul_f32 v[128:129], v[12:13], v[128:129]
	v_pk_mul_f32 v[130:131], v[14:15], v[130:131]
	v_pk_mul_f32 v[132:133], v[8:9], v[132:133]
	v_pk_mul_f32 v[134:135], v[10:11], v[134:135]
	v_pk_mul_f32 v[160:161], v[4:5], v[160:161]
	v_pk_mul_f32 v[162:163], v[6:7], v[162:163]
	v_pk_mul_f32 v[164:165], v[0:1], v[164:165]
	v_pk_mul_f32 v[166:167], v[2:3], v[166:167]
	v_cvt_pk_bf16_f32 v128, v128, v129
	v_cvt_pk_bf16_f32 v129, v130, v131
	v_cvt_pk_bf16_f32 v130, v132, v133
	v_cvt_pk_bf16_f32 v131, v134, v135
	v_cvt_pk_bf16_f32 v160, v160, v161
	global_store_dwordx4 v[168:169], v[128:131], off sc1
	v_cvt_pk_bf16_f32 v161, v162, v163
	v_cvt_pk_bf16_f32 v162, v164, v165
	v_cvt_pk_bf16_f32 v163, v166, v167
	s_nop 0
	global_store_dwordx4 v[168:169], v[160:163], off offset:256 sc1
	s_branch .Lep_done
; #define GAS __attribute__((address_space(1)))
; __device__ __forceinline__ float fsigmoid(float x) { return frcp(1.0f + fexp2(-x * LOG2E)); }
; #define EPI_FOR_ROWS for (int ai = 0; ai < 2; ++ai) _Pragma("unroll") for (int m = 0; m < 4; ++m)
; __device__ __forceinline__ v4u pack8(const f32x4 a, const f32x4 b) { v4u w; w.x = cvt_pk_bf16(a[0], a[1]); w.y = cvt_pk_bf16(a[2], a[3]); w.z = cvt_pk_bf16(b[0], b[1]); w.w = cvt_pk_bf16(b[2], b[3]); return w; }
; #define NT_ST(p, v) __builtin_nontemporal_store((v), (p))
;     __device__ __forceinline__ void operator()(Acc& acc, const Unit& u, int wr, int wc, int fr, int fq, LAS unsigned char* lds) const {
;     ...
;         GAS bf16* dst = (GAS bf16*)(ws + off);
; #pragma unroll
;         EPI_FOR_ROWS { const int row = row0 + ai * 128 + m * 16;
; #pragma unroll
;             for (int bj = 0; bj < 2; ++bj) { f32x4 a = acc[ai][bj][m][0], b = acc[ai][bj][m][1];
;                 if (act) {
; #pragma unroll
;                     for (int j = 0; j < 4; ++j) { const float sa = fsigmoid(a[j]), sb = fsigmoid(b[j]);
;                         a[j] = act == 1 ? a[j] * sa : fmaxf(sa, 1e-30f); b[j] = act == 1 ? b[j] * sb : fmaxf(sb, 1e-30f); } }
;                 NT_ST((GAS v4u*)(dst + (size_t)row * 1024 + cg0 + bj * 128), pack8(a, b)); } }
.Lep_none:
	v_cvt_pk_bf16_f32 v128, v124, v125
	v_cvt_pk_bf16_f32 v129, v126, v127
	v_cvt_pk_bf16_f32 v130, v120, v121
	v_cvt_pk_bf16_f32 v131, v122, v123
	v_cvt_pk_bf16_f32 v160, v116, v117
	v_cvt_pk_bf16_f32 v161, v118, v119
	v_cvt_pk_bf16_f32 v162, v112, v113
	v_cvt_pk_bf16_f32 v163, v114, v115
	s_nop 0
	global_store_dwordx4 v[158:159], v[128:131], off sc1
	global_store_dwordx4 v[158:159], v[160:163], off offset:256 sc1
	s_mov_b64 s[34:35], 0x8000
	v_lshl_add_u64 v[168:169], v[158:159], 0, s[34:35]
	v_cvt_pk_bf16_f32 v128, v108, v109
	v_cvt_pk_bf16_f32 v129, v110, v111
	v_cvt_pk_bf16_f32 v130, v104, v105
	v_cvt_pk_bf16_f32 v131, v106, v107
	v_cvt_pk_bf16_f32 v160, v100, v101
	v_cvt_pk_bf16_f32 v161, v102, v103
	v_cvt_pk_bf16_f32 v162, v96, v97
	v_cvt_pk_bf16_f32 v163, v98, v99
	s_nop 0
	global_store_dwordx4 v[168:169], v[128:131], off sc1
	global_store_dwordx4 v[168:169], v[160:163], off offset:256 sc1
	s_mov_b64 s[34:35], 0x10000
	v_lshl_add_u64 v[170:171], v[158:159], 0, s[34:35]
	v_cvt_pk_bf16_f32 v128, v92, v93
	v_cvt_pk_bf16_f32 v129, v94, v95
	v_cvt_pk_bf16_f32 v130, v88, v89
	v_cvt_pk_bf16_f32 v131, v90, v91
	v_cvt_pk_bf16_f32 v160, v84, v85
	v_cvt_pk_bf16_f32 v161, v86, v87
	v_cvt_pk_bf16_f32 v162, v80, v81
	v_cvt_pk_bf16_f32 v163, v82, v83
	s_nop 0
	global_store_dwordx4 v[170:171], v[128:131], off sc1
	global_store_dwordx4 v[170:171], v[160:163], off offset:256 sc1
	s_mov_b64 s[34:35], 0x18000
	v_lshl_add_u64 v[168:169], v[158:159], 0, s[34:35]
	v_cvt_pk_bf16_f32 v128, v76, v77
	v_cvt_pk_bf16_f32 v129, v78, v79
	v_cvt_pk_bf16_f32 v130, v72, v73
	v_cvt_pk_bf16_f32 v131, v74, v75
	v_cvt_pk_bf16_f32 v160, v68, v69
	v_cvt_pk_bf16_f32 v161, v70, v71
	v_cvt_pk_bf16_f32 v162, v64, v65
	v_cvt_pk_bf16_f32 v163, v66, v67
	s_nop 0
	global_store_dwordx4 v[168:169], v[128:131], off sc1
	global_store_dwordx4 v[168:169], v[160:163], off offset:256 sc1
	s_mov_b64 s[34:35], 0x40000
	v_lshl_add_u64 v[170:171], v[158:159], 0, s[34:35]
	v_cvt_pk_bf16_f32 v128, v60, v61
	v_cvt_pk_bf16_f32 v129, v62, v63
	v_cvt_pk_bf16_f32 v130, v56, v57
	v_cvt_pk_bf16_f32 v131, v58, v59
	v_cvt_pk_bf16_f32 v160, v52, v53
	v_cvt_pk_bf16_f32 v161, v54, v55
	v_cvt_pk_bf16_f32 v162, v48, v49
	v_cvt_pk_bf16_f32 v163, v50, v51
	s_nop 0
	global_store_dwordx4 v[170:171], v[128:131], off sc1
	global_store_dwordx4 v[170:171], v[160:163], off offset:256 sc1
	s_mov_b64 s[34:35], 0x48000
	v_lshl_add_u64 v[168:169], v[158:159], 0, s[34:35]
	v_cvt_pk_bf16_f32 v128, v44, v45
	v_cvt_pk_bf16_f32 v129, v46, v47
	v_cvt_pk_bf16_f32 v130, v40, v41
	v_cvt_pk_bf16_f32 v131, v42, v43
	v_cvt_pk_bf16_f32 v160, v36, v37
	v_cvt_pk_bf16_f32 v161, v38, v39
	v_cvt_pk_bf16_f32 v162, v32, v33
	v_cvt_pk_bf16_f32 v163, v34, v35
	s_nop 0
	global_store_dwordx4 v[168:169], v[128:131], off sc1
	global_store_dwordx4 v[168:169], v[160:163], off offset:256 sc1
	s_mov_b64 s[34:35], 0x50000
	v_lshl_add_u64 v[170:171], v[158:159], 0, s[34:35]
	v_cvt_pk_bf16_f32 v128, v28, v29
	v_cvt_pk_bf16_f32 v129, v30, v31
	v_cvt_pk_bf16_f32 v130, v24, v25
	v_cvt_pk_bf16_f32 v131, v26, v27
	v_cvt_pk_bf16_f32 v160, v20, v21
	v_cvt_pk_bf16_f32 v161, v22, v23
	v_cvt_pk_bf16_f32 v162, v16, v17
	v_cvt_pk_bf16_f32 v163, v18, v19
	s_nop 0
	global_store_dwordx4 v[170:171], v[128:131], off sc1
	global_store_dwordx4 v[170:171], v[160:163], off offset:256 sc1
	s_mov_b64 s[34:35], 0x58000
	v_lshl_add_u64 v[168:169], v[158:159], 0, s[34:35]
	v_cvt_pk_bf16_f32 v128, v12, v13
	v_cvt_pk_bf16_f32 v129, v14, v15
	v_cvt_pk_bf16_f32 v130, v8, v9
	v_cvt_pk_bf16_f32 v131, v10, v11
	v_cvt_pk_bf16_f32 v160, v4, v5
	v_cvt_pk_bf16_f32 v161, v6, v7
	v_cvt_pk_bf16_f32 v162, v0, v1
	v_cvt_pk_bf16_f32 v163, v2, v3
	s_nop 0
	global_store_dwordx4 v[168:169], v[128:131], off sc1
	global_store_dwordx4 v[168:169], v[160:163], off offset:256 sc1
